# tight-spin release poll: s_sleep 1 in waiter XGEN poll loop replaced by s_nop 0 (same size, offsets unchanged)
# baseline (speedup 1.0000x reference)
; __device__ __forceinline__ unsigned xb_ld(unsigned* p)              { return __hip_atomic_load(p, __ATOMIC_RELAXED, __HIP_MEMORY_SCOPE_AGENT); }
; #define XB_SPIN(cond, bar) do { unsigned _sp = 0; while (cond) { __builtin_amdgcn_s_sleep(1); \
;     if ((++_sp & 255u) == 0u) { if (xb_ld(&(bar)[XB_TMO])) break; if (_sp > XB_SPIN_CAP) { atomicAdd(&(bar)[XB_TMO], 1u); break; } } } } while (0)
; __device__ __forceinline__ void xcd_barrier(const XcdBarrier& b) {
;     ...
;     } else {
;       XB_SPIN(xb_ld(&bar[XB_XGEN(b.x)]) == gen, bar);
;       __builtin_amdgcn_fence(__ATOMIC_ACQUIRE, "agent");
;       asm volatile("s_waitcnt vmcnt(0)" ::: "memory");
;     }
.LBB0_36:
	s_and_b32 s34, s4, 0xff
	s_mov_b64 s[94:95], -1
	s_cmp_lg_u32 s34, 0
	s_mov_b64 vcc, -1
	s_nop 0
	s_cbranch_scc0 .LBB0_39
	s_and_b64 vcc, exec, vcc
	s_cbranch_vccz .LBB0_35
